# in-proj L0: CUs owning 8 (not 9) tiles start ~half a tile late so their epilogue store bursts alternate with the others'
# speedup vs baseline: 1.0129x; 1.0102x over previous
; DI int tidx() { int t = threadIdx.x; asm volatile("" : "+v"(t)); return t; }
; template <int EPI>
; DI bool tile_coords(int j, int mpx, int& m0, int& n0) {
;   const int x = blockIdx.x & 7, s = blockIdx.x >> 3, ns = gridDim.x >> 3;
;   const int q = s + ns * j;
;   if constexpr (EPI == 0) {
;     if (q >= mpx * 15) return false;
;     const int panel = q / 90, i = q % 90;
;     const int nt = i / 6, mi = i % 6;
;     m0 = (x * mpx + panel * 6 + mi) * 256;
;     n0 = nt * 256;
;   } else {
;     if (q >= mpx * 4) return false;
;     m0 = (x * mpx + (q >> 2)) * 256;
;     n0 = (q & 3) * 256;
;   }
;   return true;
; }
; template <int EPI>
; DI void gemm_phase(const P& p, int l, const u16* __restrict__ A, const u16* __restrict__ Bt, int mpx, char* lds) {
;   const int tid = tidx();
;   int t = 0;
;   int m0, n0;
;   if (!tile_coords<EPI>(t, mpx, m0, n0)) return;
;   const unsigned voffb = (unsigned)(((tid >> 3) * 1024 + (tid & 7) * 8) * 2);
;   const u16* Ag = A + (size_t)m0 * 1024;
;   const u16* Bg = Bt + (size_t)n0 * 1024;
.LBB0_74:
	s_andn2_b64 vcc, exec, s[0:1]
	s_cbranch_vccnz .LBB0_941
	s_cmp_lg_u32 s24, 1
	s_mov_b64 s[0:1], -1
	s_cbranch_scc0 .LBB0_812
	v_readlane_b32 s0, v254, 9
	v_readlane_b32 s1, v254, 10
	v_mov_b32_e32 v0, v195
	s_andn2_b64 vcc, exec, s[0:1]
	s_cbranch_vccnz .LBB0_811
	s_cmp_lg_u32 s50, 0
	s_cbranch_scc1 .Ldephase_in_done
	s_cmp_lt_u32 s84, 14
	s_cbranch_scc1 .Ldephase_in_done
	s_sleep 127
	s_sleep 127
	s_sleep 127
	s_sleep 127
.Ldephase_in_done:
	s_cmp_lg_u32 s50, 1
	s_cbranch_scc1 .Ltile_fix_done
	v_readlane_b32 s42, v254, 11
	s_lshl_b32 s43, s42, 20
	s_lshl_b32 s42, s42, 9
	v_readlane_b32 s40, v254, 58
	s_sub_i32 s40, s40, s42
	s_nop 1
	v_writelane_b32 v254, s40, 58
	v_readlane_b32 s40, v254, 61
	v_readlane_b32 s41, v254, 62
	s_sub_u32 s40, s40, s43
	s_subb_u32 s41, s41, 0
	s_nop 1
	v_writelane_b32 v254, s40, 61
	v_writelane_b32 v254, s41, 62
	v_readlane_b32 s40, v254, 63
	v_readlane_b32 s41, v255, 0
	s_sub_u32 s40, s40, s43
	s_subb_u32 s41, s41, 0
	s_nop 1
	v_writelane_b32 v254, s40, 63
	v_writelane_b32 v255, s41, 0
	v_readlane_b32 s40, v255, 1
	v_readlane_b32 s41, v255, 2
	s_sub_u32 s40, s40, s43
	s_subb_u32 s41, s41, 0
	s_nop 1
	v_writelane_b32 v255, s40, 1
	v_writelane_b32 v255, s41, 2
	v_readlane_b32 s40, v255, 3
	v_readlane_b32 s41, v255, 4
	s_sub_u32 s40, s40, s43
	s_subb_u32 s41, s41, 0
	s_nop 1
	v_writelane_b32 v255, s40, 3
	v_writelane_b32 v255, s41, 4
